# conv module: token blocks assigned XCD-contiguously (32 consecutive blocks per XCD) so the overlapping 30-row windows hit one L2
# speedup vs baseline: 1.0067x; 1.0067x over previous
.LBB0_1305:
	s_or_b64 exec, exec, s[66:67]
	s_cmpk_gt_i32 s2, 0x57f
	s_cbranch_scc1 .LBB0_1581
	v_lshlrev_b32_e32 v16, 3, v231
	v_lshlrev_b32_e32 v17, 4, v136
	s_mov_b64 s[6:7], s[22:23]
	global_load_dwordx2 v[140:141], v16, s[6:7]
	s_add_u32 s6, s6, 0x1000
	s_addc_u32 s7, s7, 0
	global_load_dwordx2 v[142:143], v16, s[6:7]
	s_add_u32 s6, s6, 0x1000
	s_addc_u32 s7, s7, 0
	global_load_dwordx2 v[144:145], v16, s[6:7]
	s_add_u32 s6, s6, 0x1000
	s_addc_u32 s7, s7, 0
	global_load_dwordx2 v[146:147], v16, s[6:7]
	s_add_u32 s6, s6, 0x1000
	s_addc_u32 s7, s7, 0
	global_load_dwordx2 v[148:149], v16, s[6:7]
	s_add_u32 s6, s6, 0x1000
	s_addc_u32 s7, s7, 0
	global_load_dwordx2 v[150:151], v16, s[6:7]
	s_add_u32 s6, s6, 0x1000
	s_addc_u32 s7, s7, 0
	global_load_dwordx2 v[152:153], v16, s[6:7]
	s_add_u32 s6, s6, 0x1000
	s_addc_u32 s7, s7, 0
	global_load_dwordx2 v[154:155], v16, s[6:7]
	s_add_u32 s6, s6, 0x1000
	s_addc_u32 s7, s7, 0
	global_load_dwordx2 v[156:157], v16, s[6:7]
	s_add_u32 s6, s6, 0x1000
	s_addc_u32 s7, s7, 0
	global_load_dwordx2 v[158:159], v16, s[6:7]
	s_add_u32 s6, s6, 0x1000
	s_addc_u32 s7, s7, 0
	global_load_dwordx2 v[160:161], v16, s[6:7]
	s_add_u32 s6, s6, 0x1000
	s_addc_u32 s7, s7, 0
	global_load_dwordx2 v[162:163], v16, s[6:7]
	s_add_u32 s6, s6, 0x1000
	s_addc_u32 s7, s7, 0
	global_load_dwordx2 v[164:165], v16, s[6:7]
	s_add_u32 s6, s6, 0x1000
	s_addc_u32 s7, s7, 0
	global_load_dwordx2 v[166:167], v16, s[6:7]
	s_add_u32 s6, s6, 0x1000
	s_addc_u32 s7, s7, 0
	global_load_dwordx2 v[168:169], v16, s[6:7]
	s_add_u32 s6, s6, 0x1000
	s_addc_u32 s7, s7, 0
	global_load_dwordx2 v[170:171], v16, s[6:7]
	s_add_u32 s6, s6, 0x1000
	s_addc_u32 s7, s7, 0
	global_load_dwordx2 v[172:173], v16, s[6:7]
	s_add_u32 s6, s6, 0x1000
	s_addc_u32 s7, s7, 0
	global_load_dwordx2 v[174:175], v16, s[6:7]
	s_add_u32 s6, s6, 0x1000
	s_addc_u32 s7, s7, 0
	global_load_dwordx2 v[176:177], v16, s[6:7]
	s_add_u32 s6, s6, 0x1000
	s_addc_u32 s7, s7, 0
	global_load_dwordx2 v[178:179], v16, s[6:7]
	s_add_u32 s6, s6, 0x1000
	s_addc_u32 s7, s7, 0
	global_load_dwordx2 v[180:181], v16, s[6:7]
	s_add_u32 s6, s6, 0x1000
	s_addc_u32 s7, s7, 0
	global_load_dwordx2 v[182:183], v16, s[6:7]
	s_add_u32 s6, s6, 0x1000
	s_addc_u32 s7, s7, 0
	global_load_dwordx2 v[184:185], v16, s[6:7]
	s_add_u32 s6, s6, 0x1000
	s_addc_u32 s7, s7, 0
	global_load_dwordx2 v[186:187], v16, s[6:7]
	s_add_u32 s6, s6, 0x1000
	s_addc_u32 s7, s7, 0
	global_load_dwordx2 v[188:189], v16, s[6:7]
	s_add_u32 s6, s6, 0x1000
	s_addc_u32 s7, s7, 0
	global_load_dwordx2 v[190:191], v16, s[6:7]
	s_add_u32 s6, s6, 0x1000
	s_addc_u32 s7, s7, 0
	global_load_dwordx2 v[192:193], v16, s[6:7]
	s_add_u32 s6, s6, 0x1000
	s_addc_u32 s7, s7, 0
	global_load_dwordx2 v[194:195], v16, s[6:7]
	s_add_u32 s6, s6, 0x1000
	s_addc_u32 s7, s7, 0
	global_load_dwordx2 v[196:197], v16, s[6:7]
	s_add_u32 s6, s6, 0x1000
	s_addc_u32 s7, s7, 0
	global_load_dwordx2 v[198:199], v16, s[6:7]
	s_add_u32 s6, s6, 0x1000
	s_addc_u32 s7, s7, 0
	global_load_dwordx2 v[200:201], v16, s[6:7]
	s_add_u32 s6, s6, 0x1000
	s_addc_u32 s7, s7, 0
	global_load_dwordx2 v[202:203], v16, s[24:25]
	global_load_dwordx4 v[204:207], v17, s[26:27] offset:0
	global_load_dwordx4 v[208:211], v17, s[26:27] offset:1024
	global_load_dwordx4 v[212:215], v17, s[26:27] offset:2048
	global_load_dwordx4 v[216:219], v17, s[26:27] offset:3072
	global_load_dwordx4 v[240:243], v17, s[36:37] offset:0
	global_load_dwordx4 v[244:247], v17, s[36:37] offset:1024
	global_load_dwordx4 v[248:251], v17, s[36:37] offset:2048
	global_load_dwordx4 v[124:127], v17, s[36:37] offset:3072
	global_load_dwordx4 v[128:131], v17, s[70:71] offset:0
	global_load_dwordx4 v[132:135], v17, s[70:71] offset:1024
	global_load_dwordx4 v[0:3], v17, s[70:71] offset:2048
	global_load_dwordx4 v[4:7], v17, s[70:71] offset:3072
	v_lshl_add_u32 v17, v230, 12, v17
	v_lshlrev_b32_e32 v19, 3, v136
	v_lshl_add_u32 v19, v230, 12, v19
	v_add_u32_e32 v19, 0x800, v19
	s_and_b32 s3, s2, 7
	s_lshl_b32 s3, s3, 5
	s_lshr_b32 s80, s2, 3
	s_add_i32 s3, s3, s80
	s_lshl_b32 s80, s3, 3
	s_sub_i32 s80, 30, s80
	s_lshl_b32 s3, s3, 15
	s_add_u32 s66, s42, 0x29700000
	s_addc_u32 s67, s43, 0
	s_add_u32 s66, s66, s3
	s_addc_u32 s67, s67, 0
	s_sub_u32 s66, s66, 0x1e000
	s_subb_u32 s67, s67, 0
	s_add_u32 s8, s42, 0x2bf00000
	s_addc_u32 s9, s43, 0
	s_add_u32 s8, s8, s3
	s_addc_u32 s9, s9, 0
	s_waitcnt vmcnt(0)
	s_mov_b64 s[6:7], s[66:67]
	s_cmp_gt_i32 s80, 0
	s_cbranch_scc1 .Lcv_z_1
	global_load_dwordx2 v[32:33], v16, s[6:7]
	s_branch .Lcv_n_2
